# speedup vs baseline: 1.0054x; 1.0054x over previous
; __device__ __forceinline__ void finishSM(f32x16& p0, f32x16& p1, float alpha, float& l_reg, bf16x8& pa0, bf16x8& pa1, bf16x8& pa2, bf16x8& pa3) {
;     for (int r = 0; r < 16; ++r) p1[r] = __builtin_amdgcn_exp2f(p1[r]);
;     float ps = 0; for (int r = 0; r < 16; ++r) ps += p0[r]; for (int r = 0; r < 16; ++r) ps += p1[r];
;     { auto rr = __builtin_amdgcn_permlane32_swap(__float_as_uint(ps), __float_as_uint(ps), false, false);
;       ps = __uint_as_float(rr[0]) + __uint_as_float(rr[1]); }
;     l_reg = l_reg * alpha + ps;
.LBB0_251:
	s_or_b64 exec, exec, s[10:11]
	s_waitcnt lgkmcnt(0)
	s_waitcnt vmcnt(2)
	ds_read_b128 v[162:165], v207 offset:224
	s_waitcnt vmcnt(1)
	ds_read_b128 v[166:169], v207 offset:192
	s_waitcnt vmcnt(0)
	ds_read_b128 v[170:173], v207 offset:160
	ds_read_b128 v[64:67], v207 offset:128
	s_waitcnt lgkmcnt(3)
	v_pk_mul_f32 v[14:15], v[14:15], v[164:165]
	s_waitcnt lgkmcnt(2)
	v_pk_mul_f32 v[10:11], v[10:11], v[168:169]
	s_waitcnt lgkmcnt(1)
	v_pk_mul_f32 v[6:7], v[6:7], v[172:173]
	s_waitcnt lgkmcnt(0)
	v_pk_mul_f32 v[2:3], v[2:3], v[66:67]
	v_pk_mul_f32 v[12:13], v[12:13], v[162:163]
	v_pk_mul_f32 v[8:9], v[8:9], v[166:167]
	v_pk_mul_f32 v[4:5], v[4:5], v[170:171]
	v_pk_mul_f32 v[0:1], v[0:1], v[64:65]
	v_pk_mul_f32 v[62:63], v[62:63], v[164:165]
	v_pk_mul_f32 v[58:59], v[58:59], v[168:169]
	v_pk_mul_f32 v[54:55], v[54:55], v[172:173]
	v_pk_mul_f32 v[50:51], v[50:51], v[66:67]
	v_pk_mul_f32 v[60:61], v[60:61], v[162:163]
	v_pk_mul_f32 v[56:57], v[56:57], v[166:167]
	v_pk_mul_f32 v[52:53], v[52:53], v[170:171]
	v_pk_mul_f32 v[48:49], v[48:49], v[64:65]
	v_pk_mul_f32 v[46:47], v[46:47], v[164:165]
	v_pk_mul_f32 v[42:43], v[42:43], v[168:169]
	v_pk_mul_f32 v[38:39], v[38:39], v[172:173]
	v_pk_mul_f32 v[34:35], v[34:35], v[66:67]
	v_pk_mul_f32 v[44:45], v[44:45], v[162:163]
	v_pk_mul_f32 v[40:41], v[40:41], v[166:167]
	v_pk_mul_f32 v[36:37], v[36:37], v[170:171]
	v_pk_mul_f32 v[32:33], v[32:33], v[64:65]
	v_pk_mul_f32 v[30:31], v[30:31], v[164:165]
	v_pk_mul_f32 v[26:27], v[26:27], v[168:169]
	v_pk_mul_f32 v[22:23], v[22:23], v[172:173]
	v_pk_mul_f32 v[18:19], v[18:19], v[66:67]
	v_pk_mul_f32 v[28:29], v[28:29], v[162:163]
	v_pk_mul_f32 v[24:25], v[24:25], v[166:167]
	v_pk_mul_f32 v[20:21], v[20:21], v[170:171]
	v_pk_mul_f32 v[16:17], v[16:17], v[64:65]
.LBB0_252:
	v_add_f32_e32 v96, v224, v225
	v_fmac_f32_e32 v96, v218, v191
	v_add_f32_e32 v191, v240, v241
	s_addk_i32 s96, 0x80
	s_add_i32 s83, s83, 2
	v_fmac_f32_e32 v191, v96, v226
	s_cmp_ge_i32 s83, s89
	v_add_u32_e32 v223, 0xffffff80, v223
	v_mov_b32_e32 v218, v160
	s_waitcnt lgkmcnt(0)
	s_barrier
	s_cbranch_scc1 .LBB0_276

; __device__ __forceinline__ void finishSM(f32x16& p0, f32x16& p1, float alpha, float& l_reg, bf16x8& pa0, bf16x8& pa1, bf16x8& pa2, bf16x8& pa3) {
;     for (int r = 0; r < 16; ++r) p1[r] = __builtin_amdgcn_exp2f(p1[r]);
;     float ps = 0; for (int r = 0; r < 16; ++r) ps += p0[r]; for (int r = 0; r < 16; ++r) ps += p1[r];
;     { auto rr = __builtin_amdgcn_permlane32_swap(__float_as_uint(ps), __float_as_uint(ps), false, false);
;       ps = __uint_as_float(rr[0]) + __uint_as_float(rr[1]); }
;     l_reg = l_reg * alpha + ps;
;     ...
;     PK4(p0, 0, pa0); PK4(p0, 8, pa1); PK4(p1, 0, pa2); PK4(p1, 8, pa3);
;     ...
; }
; template <int KB>
; __device__ __forceinline__ void qkt(f32x16& p0, f32x16& p1, const char* K_lds, const float* bias_l, int r32, int hi, const bf16x8* qr) {
;     const f32x4* bl = reinterpret_cast<const f32x4*>(bias_l + KB * 64);
; #pragma unroll
;     for (int g = 0; g < 4; ++g) { const f32x4 b0 = bl[2 * g + hi], b1 = bl[8 + 2 * g + hi];
;         p0[4 * g + 0] = b0[0]; p0[4 * g + 1] = b0[1]; p0[4 * g + 2] = b0[2]; p0[4 * g + 3] = b0[3];
;         p1[4 * g + 0] = b1[0]; p1[4 * g + 1] = b1[1]; p1[4 * g + 2] = b1[2]; p1[4 * g + 3] = b1[3]; }
;     const char* kb[4];
; #pragma unroll
;     for (int dd = 0; dd < 4; ++dd) kb[dd] = K_lds + KB * SHM_K + KSWZ(r32, (dd * 16 + hi * 8) * 2);
; #pragma unroll
;     for (int d0 = 0; d0 < 8; ++d0) { const char* a = kb[d0 & 3] + (d0 >> 2) * 128;
;         bf16x8 b0 = *reinterpret_cast<const bf16x8*>(a);
;         bf16x8 b1 = *reinterpret_cast<const bf16x8*>(a + 32 * 256);
;         p0 = __builtin_amdgcn_mfma_f32_32x32x16_bf16(b0, qr[d0], p0, 0, 0, 0);
;         p1 = __builtin_amdgcn_mfma_f32_32x32x16_bf16(b1, qr[d0], p1, 0, 0, 0); }
; }
.LBB0_255:
	ds_read_b128 v[84:87], v220
	ds_read_b128 v[88:91], v220 offset:32
	ds_read_b128 v[68:71], v220 offset:128
	ds_read_b128 v[72:75], v220 offset:160
	ds_read_b128 v[92:95], v220 offset:64
	ds_read_b128 v[76:79], v220 offset:192
	ds_read_b128 v[96:99], v220 offset:96
	ds_read_b128 v[80:83], v220 offset:224
	ds_read_b128 v[196:199], v214 offset:49152
	ds_read_b128 v[242:245], v214 offset:57344
	ds_read_b128 v[246:249], v215 offset:49152
	ds_read_b128 v[250:253], v215 offset:57344
	v_exp_f32_e32 v104, v126
	v_exp_f32_e32 v105, v127
	v_exp_f32_e32 v106, v124
	v_exp_f32_e32 v107, v125
	v_exp_f32_e32 v108, v122
	v_exp_f32_e32 v109, v123
	v_exp_f32_e32 v110, v120
	v_exp_f32_e32 v111, v121
	v_exp_f32_e32 v118, v118
	v_exp_f32_e32 v119, v119
	v_exp_f32_e32 v116, v116
	v_exp_f32_e32 v117, v117
	v_exp_f32_e32 v114, v114
	v_exp_f32_e32 v115, v115
	v_exp_f32_e32 v112, v112
	v_exp_f32_e32 v113, v113
	v_add_f32_e32 v64, 0, v237
	v_add_f32_e32 v64, v239, v64
	v_add_f32_e32 v64, v235, v64
	v_add_f32_e32 v64, v238, v64
	v_add_f32_e32 v64, v234, v64
	v_add_f32_e32 v64, v236, v64
	v_add_f32_e32 v64, v232, v64
	v_add_f32_e32 v64, v233, v64
	v_add_f32_e32 v64, v228, v64
	v_add_f32_e32 v64, v231, v64
	v_add_f32_e32 v64, v179, v64
	v_add_f32_e32 v64, v229, v64
	s_waitcnt lgkmcnt(3)
	v_mfma_f32_32x32x16_bf16 v[84:99], v[196:199], v[156:159], v[84:99]
	v_add_f32_e32 v64, v177, v64
	v_add_f32_e32 v64, v230, v64
	v_add_f32_e32 v64, v178, v64
	s_waitcnt lgkmcnt(2)
	v_mfma_f32_32x32x16_bf16 v[68:83], v[242:245], v[156:159], v[68:83]
	v_add_f32_e32 v64, v227, v64
	v_add_f32_e32 v64, v104, v64
	v_add_f32_e32 v64, v105, v64
	ds_read_b128 v[196:199], v213 offset:49152
	ds_read_b128 v[242:245], v213 offset:57344
	s_waitcnt lgkmcnt(3)
	v_mfma_f32_32x32x16_bf16 v[84:99], v[246:249], v[152:155], v[84:99]
	v_add_f32_e32 v64, v106, v64
	v_add_f32_e32 v64, v107, v64
	v_add_f32_e32 v64, v108, v64
	s_waitcnt lgkmcnt(2)
	v_mfma_f32_32x32x16_bf16 v[68:83], v[250:253], v[152:155], v[68:83]
	v_add_f32_e32 v64, v109, v64
	v_add_f32_e32 v64, v110, v64
	v_add_f32_e32 v64, v111, v64
	ds_read_b128 v[246:249], v212 offset:49152
	ds_read_b128 v[250:253], v212 offset:57344
	s_waitcnt lgkmcnt(3)
	v_mfma_f32_32x32x16_bf16 v[84:99], v[196:199], v[148:151], v[84:99]
	v_add_f32_e32 v64, v118, v64
	v_add_f32_e32 v64, v119, v64
	v_add_f32_e32 v64, v116, v64
	s_waitcnt lgkmcnt(2)
	v_mfma_f32_32x32x16_bf16 v[68:83], v[242:245], v[148:151], v[68:83]
	v_add_f32_e32 v64, v117, v64
	v_add_f32_e32 v64, v114, v64
	v_add_f32_e32 v64, v115, v64
	ds_read_b128 v[196:199], v214 offset:49280
	ds_read_b128 v[242:245], v214 offset:57472
	s_waitcnt lgkmcnt(3)
	v_mfma_f32_32x32x16_bf16 v[84:99], v[246:249], v[144:147], v[84:99]
	v_add_f32_e32 v64, v112, v64
	v_add_f32_e32 v224, v113, v64
	v_mov_b32_e32 v225, v224
	s_nop 1
	v_permlane32_swap_b32_e32 v224, v225
	s_waitcnt lgkmcnt(2)
	v_mfma_f32_32x32x16_bf16 v[68:83], v[250:253], v[144:147], v[68:83]
	v_cvt_pk_bf16_f32 v64, v237, v239
	v_cvt_pk_bf16_f32 v65, v235, v238
	v_cvt_pk_bf16_f32 v66, v234, v236
	ds_read_b128 v[246:249], v215 offset:49280
	ds_read_b128 v[250:253], v215 offset:57472
	s_waitcnt lgkmcnt(3)
	v_mfma_f32_32x32x16_bf16 v[84:99], v[196:199], v[140:143], v[84:99]
	v_cvt_pk_bf16_f32 v67, v232, v233
	v_cvt_pk_bf16_f32 v100, v228, v231
	v_cvt_pk_bf16_f32 v101, v179, v229
	s_waitcnt lgkmcnt(2)
	v_mfma_f32_32x32x16_bf16 v[68:83], v[242:245], v[140:143], v[68:83]
	v_cvt_pk_bf16_f32 v102, v177, v230
	v_cvt_pk_bf16_f32 v103, v178, v227
	v_cvt_pk_bf16_f32 v104, v104, v105
	ds_read_b128 v[196:199], v213 offset:49280
	ds_read_b128 v[242:245], v213 offset:57472
	s_waitcnt lgkmcnt(3)
	v_mfma_f32_32x32x16_bf16 v[84:99], v[246:249], v[136:139], v[84:99]
	v_cvt_pk_bf16_f32 v105, v106, v107
	v_cvt_pk_bf16_f32 v106, v108, v109
	v_cvt_pk_bf16_f32 v107, v110, v111
	s_waitcnt lgkmcnt(2)
	v_mfma_f32_32x32x16_bf16 v[68:83], v[250:253], v[136:139], v[68:83]
	v_cvt_pk_bf16_f32 v108, v118, v119
	v_cvt_pk_bf16_f32 v109, v116, v117
	v_cvt_pk_bf16_f32 v110, v114, v115
	ds_read_b128 v[246:249], v212 offset:49280
	ds_read_b128 v[250:253], v212 offset:57472
	s_waitcnt lgkmcnt(3)
	v_mfma_f32_32x32x16_bf16 v[84:99], v[196:199], v[132:135], v[84:99]
	v_cvt_pk_bf16_f32 v111, v112, v113
	s_nop 0
	v_permlane32_swap_b32_e32 v64, v66
	s_waitcnt lgkmcnt(2)
	v_mfma_f32_32x32x16_bf16 v[68:83], v[242:245], v[132:135], v[68:83]
	v_permlane32_swap_b32_e32 v65, v67
	v_permlane32_swap_b32_e32 v100, v102
	v_permlane32_swap_b32_e32 v101, v103
	ds_read_b64_tr_b16 v[112:113], v209 offset:0x0
	ds_read_b64_tr_b16 v[114:115], v209 offset:0x800
	ds_read_b64_tr_b16 v[116:117], v209 offset:0x1000
	ds_read_b64_tr_b16 v[118:119], v209 offset:0x1800
	ds_read_b64_tr_b16 v[120:121], v209 offset:0x2000
	ds_read_b64_tr_b16 v[122:123], v209 offset:0x2800
	ds_read_b64_tr_b16 v[124:125], v209 offset:0x3000
	ds_read_b64_tr_b16 v[126:127], v209 offset:0x3800
	s_waitcnt lgkmcnt(9)
	v_mfma_f32_32x32x16_bf16 v[84:99], v[246:249], v[128:131], v[84:99]
	v_permlane32_swap_b32_e32 v104, v106
	v_permlane32_swap_b32_e32 v105, v107
	v_permlane32_swap_b32_e32 v108, v110
	s_waitcnt lgkmcnt(8)
	v_mfma_f32_32x32x16_bf16 v[68:83], v[250:253], v[128:131], v[68:83]
	v_permlane32_swap_b32_e32 v109, v111
	s_add_i32 s12, s96, 0xffffffbf
	s_cmp_le_i32 s12, s84
	s_cbranch_scc1 .Lhs1_nomask
; __device__ __forceinline__ void mask_tile(f32x16& p0, f32x16& p1, int dq, unsigned W) {
;     const float NEG = -__builtin_inff();
; #pragma unroll
;     for (int r = 0; r < 16; ++r) {
;         const int c = (r & 3) + 8 * (r >> 2);
;         if ((unsigned)(dq - c) >= W) p0[r] = NEG;
;         if ((unsigned)(dq - c - 32) >= W) p1[r] = NEG;
;     }
; }
; __device__ __forceinline__ void partialSM(f32x16& p0, f32x16& p1, float& m_reg, float& mn, float& alpha) {
;     float pmax = p0[0]; for (int r = 1; r < 16; ++r) pmax = fmaxf(pmax, p0[r]); for (int r = 0; r < 16; ++r) pmax = fmaxf(pmax, p1[r]);
;     { auto rr = __builtin_amdgcn_permlane32_swap(__float_as_uint(pmax), __float_as_uint(pmax), false, false);
;       pmax = fmaxf(__uint_as_float(rr[0]), __uint_as_float(rr[1])); }
	v_add_u32_e32 v250, 64, v223
	v_cmp_gt_i32_e64 s[72:73], 26, v250
	v_cmp_gt_i32_e64 s[74:75], 27, v250
	v_cmp_gt_i32_e64 s[70:71], 25, v250
	s_and_b64 s[72:73], s[74:75], s[72:73]
	v_cmp_gt_i32_e64 s[68:69], 24, v250
	s_and_b64 s[70:71], s[72:73], s[70:71]
	v_cmp_gt_i32_e64 s[66:67], 19, v250
	s_and_b64 s[68:69], s[70:71], s[68:69]
	v_cmp_gt_i32_e64 s[64:65], 18, v250
	s_and_b64 s[66:67], s[68:69], s[66:67]
	v_cmp_gt_i32_e64 s[62:63], 17, v250
	s_and_b64 s[64:65], s[66:67], s[64:65]
	v_cmp_gt_i32_e64 s[60:61], 16, v250
	s_and_b64 s[62:63], s[64:65], s[62:63]
	v_cmp_gt_i32_e64 s[58:59], 11, v250
	s_and_b64 s[60:61], s[62:63], s[60:61]
	v_cmp_gt_i32_e64 s[56:57], 10, v250
	s_and_b64 s[58:59], s[60:61], s[58:59]
	v_cmp_gt_i32_e64 s[54:55], 9, v250
	s_and_b64 s[56:57], s[58:59], s[56:57]
	v_cmp_gt_i32_e64 s[52:53], 8, v250
	s_and_b64 s[54:55], s[56:57], s[54:55]
	v_cmp_gt_i32_e64 s[50:51], 3, v250
	s_and_b64 s[52:53], s[54:55], s[52:53]
	v_cmp_gt_i32_e64 s[48:49], 2, v250
	s_and_b64 s[50:51], s[52:53], s[50:51]
	v_cmp_gt_i32_e64 s[46:47], 1, v250
	s_and_b64 s[48:49], s[50:51], s[48:49]
	v_cmp_gt_i32_e64 s[44:45], 0, v250
	s_and_b64 s[46:47], s[48:49], s[46:47]
	s_and_b64 s[44:45], s[46:47], s[44:45]
	v_cmp_gt_i32_e64 s[40:41], 58, v250
	v_cndmask_b32_e64 v84, v84, v205, s[44:45]
	v_cmp_gt_i32_e64 s[44:45], 59, v250
	v_cmp_gt_i32_e64 s[38:39], 57, v250
	s_and_b64 s[40:41], s[44:45], s[40:41]
	v_cmp_gt_i32_e64 s[36:37], 56, v250
	s_and_b64 s[38:39], s[40:41], s[38:39]
	v_cmp_gt_i32_e64 s[34:35], 51, v250
	s_and_b64 s[36:37], s[38:39], s[36:37]
	v_cmp_gt_i32_e64 s[30:31], 50, v250
	s_and_b64 s[34:35], s[36:37], s[34:35]
	v_cmp_gt_i32_e64 s[28:29], 49, v250
	s_and_b64 s[30:31], s[34:35], s[30:31]
	v_cmp_gt_i32_e64 s[26:27], 48, v250
	s_and_b64 s[28:29], s[30:31], s[28:29]
	v_cmp_gt_i32_e64 s[24:25], 43, v250
	s_and_b64 s[26:27], s[28:29], s[26:27]
	v_cmp_gt_i32_e64 s[22:23], 42, v250
	s_and_b64 s[24:25], s[26:27], s[24:25]
	v_cmp_gt_i32_e64 s[20:21], 41, v250
	s_and_b64 s[22:23], s[24:25], s[22:23]
	v_cmp_gt_i32_e64 s[18:19], 40, v250
	s_and_b64 s[20:21], s[22:23], s[20:21]
	v_cmp_gt_i32_e64 s[16:17], 35, v250
	s_and_b64 s[18:19], s[20:21], s[18:19]
	v_cmp_gt_i32_e64 s[14:15], 34, v250
	s_and_b64 s[16:17], s[18:19], s[16:17]
	v_cmp_gt_i32_e64 s[12:13], 33, v250
	s_and_b64 s[14:15], s[16:17], s[14:15]
	v_cmp_gt_i32_e32 vcc, 32, v250
	s_and_b64 s[12:13], s[14:15], s[12:13]
	s_and_b64 vcc, s[12:13], vcc
	v_cndmask_b32_e64 v99, v99, v205, s[74:75]
	v_cndmask_b32_e64 v98, v98, v205, s[72:73]
	v_cndmask_b32_e64 v97, v97, v205, s[70:71]
	v_cndmask_b32_e64 v96, v96, v205, s[68:69]
	v_cndmask_b32_e64 v95, v95, v205, s[66:67]
	v_cndmask_b32_e64 v94, v94, v205, s[64:65]
	v_cndmask_b32_e64 v93, v93, v205, s[62:63]
	v_cndmask_b32_e64 v92, v92, v205, s[60:61]
	v_cndmask_b32_e64 v91, v91, v205, s[58:59]
	v_cndmask_b32_e64 v90, v90, v205, s[56:57]
	v_cndmask_b32_e64 v89, v89, v205, s[54:55]
	v_cndmask_b32_e64 v88, v88, v205, s[52:53]
	v_cndmask_b32_e64 v87, v87, v205, s[50:51]
	v_cndmask_b32_e64 v86, v86, v205, s[48:49]
	v_cndmask_b32_e64 v85, v85, v205, s[46:47]
	v_cndmask_b32_e64 v83, v83, v205, s[44:45]
	v_cndmask_b32_e64 v82, v82, v205, s[40:41]
	v_cndmask_b32_e64 v81, v81, v205, s[38:39]
	v_cndmask_b32_e64 v80, v80, v205, s[36:37]
	v_cndmask_b32_e64 v79, v79, v205, s[34:35]
	v_cndmask_b32_e64 v78, v78, v205, s[30:31]
	v_cndmask_b32_e64 v77, v77, v205, s[28:29]
	v_cndmask_b32_e64 v76, v76, v205, s[26:27]
	v_cndmask_b32_e64 v75, v75, v205, s[24:25]
	v_cndmask_b32_e64 v74, v74, v205, s[22:23]
	v_cndmask_b32_e64 v73, v73, v205, s[20:21]
	v_cndmask_b32_e64 v72, v72, v205, s[18:19]
	v_cndmask_b32_e64 v71, v71, v205, s[16:17]
	v_cndmask_b32_e64 v70, v70, v205, s[14:15]
	v_cndmask_b32_e64 v69, v69, v205, s[12:13]
	v_cndmask_b32_e32 v68, v68, v205, vcc
.Lhs1_nomask:
	s_waitcnt lgkmcnt(6)
	v_mfma_f32_32x32x16_bf16 v[0:15], v[64:67], v[112:115], v[0:15]
	ds_read_b64_tr_b16 v[112:113], v209 offset:0x200
	ds_read_b64_tr_b16 v[114:115], v209 offset:0xa00
	s_waitcnt lgkmcnt(6)
	v_mfma_f32_32x32x16_bf16 v[0:15], v[100:103], v[116:119], v[0:15]
	ds_read_b64_tr_b16 v[116:117], v209 offset:0x1200
	ds_read_b64_tr_b16 v[118:119], v209 offset:0x1a00
	s_waitcnt lgkmcnt(6)
	v_mfma_f32_32x32x16_bf16 v[0:15], v[104:107], v[120:123], v[0:15]
	ds_read_b64_tr_b16 v[120:121], v209 offset:0x2200
	ds_read_b64_tr_b16 v[122:123], v209 offset:0x2a00
	v_max_f32_e32 v250, v85, v85
	v_max_f32_e32 v251, v84, v84
	v_max_f32_e32 v250, v251, v250
	v_max3_f32 v250, v250, v86, v87
	v_max3_f32 v250, v250, v88, v89
	v_max3_f32 v250, v250, v90, v91
	v_max3_f32 v250, v250, v92, v93
	s_waitcnt lgkmcnt(6)
	v_mfma_f32_32x32x16_bf16 v[0:15], v[108:111], v[124:127], v[0:15]
	ds_read_b64_tr_b16 v[124:125], v209 offset:0x3200
	ds_read_b64_tr_b16 v[126:127], v209 offset:0x3a00
	v_max3_f32 v250, v250, v94, v95
	v_max3_f32 v250, v250, v96, v97
	v_max3_f32 v250, v250, v98, v99
	v_max3_f32 v250, v250, v68, v69
	v_max3_f32 v250, v250, v70, v71
	v_max3_f32 v250, v250, v72, v73
	v_max3_f32 v250, v250, v74, v75
	s_waitcnt lgkmcnt(6)
	v_mfma_f32_32x32x16_bf16 v[48:63], v[64:67], v[112:115], v[48:63]
	ds_read_b64_tr_b16 v[112:113], v209 offset:0x400
	ds_read_b64_tr_b16 v[114:115], v209 offset:0xc00
	v_max3_f32 v250, v250, v76, v77
	v_max3_f32 v250, v250, v78, v79
	v_max3_f32 v250, v250, v80, v81
	v_max3_f32 v250, v250, v82, v83
	v_mov_b32_e32 v251, v250
	s_nop 1
	v_permlane32_swap_b32_e32 v250, v251
	v_max_f32_e32 v251, v251, v251
	s_waitcnt lgkmcnt(6)
; __device__ __forceinline__ void partialSM(f32x16& p0, f32x16& p1, float& m_reg, float& mn, float& alpha) {
;     float pmax = p0[0]; for (int r = 1; r < 16; ++r) pmax = fmaxf(pmax, p0[r]); for (int r = 0; r < 16; ++r) pmax = fmaxf(pmax, p1[r]);
;     { auto rr = __builtin_amdgcn_permlane32_swap(__float_as_uint(pmax), __float_as_uint(pmax), false, false);
;       pmax = fmaxf(__uint_as_float(rr[0]), __uint_as_float(rr[1])); }
;     constexpr float C2 = 1.4426950408889634f * SCALE;
;     if (__builtin_expect(__all((pmax - m_reg) * SCALE <= THR), 1)) { mn = m_reg; alpha = 1.f; }
;     else { mn = fmaxf(m_reg, pmax); alpha = __builtin_amdgcn_exp2f((m_reg - mn) * C2); m_reg = mn; }
;     const float mnL = -mn * C2;
;     for (int r = 0; r < 16; ++r) p0[r] = fmaf(p0[r], C2, mnL); for (int r = 0; r < 16; ++r) p1[r] = fmaf(p1[r], C2, mnL);
;     for (int r = 0; r < 16; ++r) p0[r] = __builtin_amdgcn_exp2f(p0[r]);
; }
	v_mfma_f32_32x32x16_bf16 v[48:63], v[100:103], v[116:119], v[48:63]
	ds_read_b64_tr_b16 v[116:117], v209 offset:0x1400
	ds_read_b64_tr_b16 v[118:119], v209 offset:0x1c00
	v_max_f32_e32 v250, v250, v250
	v_max_f32_e32 v250, v250, v251
	v_sub_f32_e32 v251, v250, v176
	v_mul_f32_e32 v251, 0x3db504f3, v251
	v_cmp_ge_f32_e32 vcc, s97, v251
	s_cmp_eq_u64 vcc, exec
	s_cselect_b64 s[12:13], -1, 0
	v_max_f32_e32 v251, v176, v176
	s_waitcnt lgkmcnt(6)
	v_mfma_f32_32x32x16_bf16 v[48:63], v[104:107], v[120:123], v[48:63]
	ds_read_b64_tr_b16 v[120:121], v209 offset:0x2400
	ds_read_b64_tr_b16 v[122:123], v209 offset:0x2c00
	v_max_f32_e32 v250, v251, v250
	v_sub_f32_e32 v251, v176, v250
	v_mul_f32_e32 v251, 0x3e0293ee, v251
	v_exp_f32_e32 v251, v251
	s_nop 0
	v_cndmask_b32_e64 v226, v251, 1.0, s[12:13]
	v_cndmask_b32_e64 v227, v250, v176, s[12:13]
	s_waitcnt lgkmcnt(6)
	v_mfma_f32_32x32x16_bf16 v[48:63], v[108:111], v[124:127], v[48:63]
	ds_read_b64_tr_b16 v[124:125], v209 offset:0x3400
	ds_read_b64_tr_b16 v[126:127], v209 offset:0x3c00
	v_mul_f32_e32 v176, 0xbe0293ee, v227
	v_fmamk_f32 v196, v84, 0x3e0293ee, v176
	v_fmamk_f32 v197, v85, 0x3e0293ee, v176
	v_fmamk_f32 v198, v86, 0x3e0293ee, v176
	v_fmamk_f32 v199, v87, 0x3e0293ee, v176
	v_fmamk_f32 v242, v88, 0x3e0293ee, v176
	v_fmamk_f32 v243, v89, 0x3e0293ee, v176
	s_waitcnt lgkmcnt(6)
	v_mfma_f32_32x32x16_bf16 v[32:47], v[64:67], v[112:115], v[32:47]
	ds_read_b64_tr_b16 v[112:113], v209 offset:0x600
	ds_read_b64_tr_b16 v[114:115], v209 offset:0xe00
	v_fmamk_f32 v244, v90, 0x3e0293ee, v176
	v_fmamk_f32 v245, v91, 0x3e0293ee, v176
	v_fmamk_f32 v246, v92, 0x3e0293ee, v176
	v_fmamk_f32 v247, v93, 0x3e0293ee, v176
	v_fmamk_f32 v248, v94, 0x3e0293ee, v176
	v_fmamk_f32 v249, v95, 0x3e0293ee, v176
	v_fmamk_f32 v96, v96, 0x3e0293ee, v176
	s_waitcnt lgkmcnt(6)
	v_mfma_f32_32x32x16_bf16 v[32:47], v[100:103], v[116:119], v[32:47]
	ds_read_b64_tr_b16 v[116:117], v209 offset:0x1600
	ds_read_b64_tr_b16 v[118:119], v209 offset:0x1e00
	v_fmamk_f32 v97, v97, 0x3e0293ee, v176
	v_fmamk_f32 v98, v98, 0x3e0293ee, v176
	v_fmamk_f32 v99, v99, 0x3e0293ee, v176
	v_fmamk_f32 v84, v68, 0x3e0293ee, v176
	v_fmamk_f32 v93, v69, 0x3e0293ee, v176
	v_fmamk_f32 v94, v70, 0x3e0293ee, v176
	v_fmamk_f32 v95, v71, 0x3e0293ee, v176
	s_waitcnt lgkmcnt(6)
	v_mfma_f32_32x32x16_bf16 v[32:47], v[104:107], v[120:123], v[32:47]
	ds_read_b64_tr_b16 v[120:121], v209 offset:0x2600
	ds_read_b64_tr_b16 v[122:123], v209 offset:0x2e00
	v_fmamk_f32 v177, v72, 0x3e0293ee, v176
	v_fmamk_f32 v85, v73, 0x3e0293ee, v176
	v_fmamk_f32 v86, v74, 0x3e0293ee, v176
	v_fmamk_f32 v87, v75, 0x3e0293ee, v176
	v_fmamk_f32 v88, v76, 0x3e0293ee, v176
	v_fmamk_f32 v89, v77, 0x3e0293ee, v176
	v_fmamk_f32 v90, v78, 0x3e0293ee, v176
	s_waitcnt lgkmcnt(6)
	v_mfma_f32_32x32x16_bf16 v[32:47], v[108:111], v[124:127], v[32:47]
	ds_read_b64_tr_b16 v[124:125], v209 offset:0x3600
	ds_read_b64_tr_b16 v[126:127], v209 offset:0x3e00
	v_fmamk_f32 v91, v79, 0x3e0293ee, v176
	v_fmamk_f32 v92, v80, 0x3e0293ee, v176
	v_fmamk_f32 v178, v81, 0x3e0293ee, v176
	v_fmamk_f32 v179, v82, 0x3e0293ee, v176
	v_fmac_f32_e32 v176, 0x3e0293ee, v83
	v_exp_f32_e32 v68, v242
	s_waitcnt lgkmcnt(6)
	v_mfma_f32_32x32x16_bf16 v[16:31], v[64:67], v[112:115], v[16:31]
	v_exp_f32_e32 v69, v243
	v_exp_f32_e32 v70, v244
	v_exp_f32_e32 v71, v245
	v_exp_f32_e32 v72, v246
	s_waitcnt lgkmcnt(4)
	v_mfma_f32_32x32x16_bf16 v[16:31], v[100:103], v[116:119], v[16:31]
	v_exp_f32_e32 v73, v247
	v_exp_f32_e32 v74, v248
	v_exp_f32_e32 v75, v249
	v_exp_f32_e32 v76, v96
	s_waitcnt lgkmcnt(2)
	v_mfma_f32_32x32x16_bf16 v[16:31], v[104:107], v[120:123], v[16:31]
	v_exp_f32_e32 v77, v97
	v_exp_f32_e32 v78, v98
	v_exp_f32_e32 v79, v99
	s_waitcnt lgkmcnt(0)
	v_mfma_f32_32x32x16_bf16 v[16:31], v[108:111], v[124:127], v[16:31]
	s_waitcnt vmcnt(0)
	s_and_b64 vcc, exec, s[10:11]
	ds_write_b128 v208, v[164:167] offset:32768
	ds_write_b128 v208, v[172:175] offset:40960
	s_cbranch_vccnz .Lhs1_nobias
	s_mov_b32 s14, 0x667f3bcd
	v_add_f64 v[66:67], s[94:95], -v[188:189]
	s_mov_b32 s15, 0x4026a09e
	v_mul_f64 v[66:67], v[66:67], s[14:15]
	v_cvt_f32_f64_e32 v65, v[66:67]
	ds_write_b32 v221, v65
.Lhs1_nobias:
	s_barrier
	ds_write_b128 v216, v[160:163]
	ds_write_b128 v217, v[168:171]
	v_exp_f32_e32 v64, v196
	v_exp_f32_e32 v65, v197
	v_exp_f32_e32 v66, v198
	v_exp_f32_e32 v67, v199
	v_cmp_gt_f32_e32 vcc, 1.0, v226
	s_cbranch_vccz .Lhs1_norescale
	s_and_saveexec_b64 s[14:15], s[8:9]
	ds_write_b32 v222, v226 offset:128
	s_or_b64 exec, exec, s[14:15]
	s_waitcnt lgkmcnt(0)
	ds_read_b128 v[100:103], v207 offset:224
	ds_read_b128 v[104:107], v207 offset:192
	ds_read_b128 v[108:111], v207 offset:160
	ds_read_b128 v[112:115], v207 offset:128
	s_waitcnt lgkmcnt(3)
	v_pk_mul_f32 v[14:15], v[14:15], v[102:103]
	s_waitcnt lgkmcnt(2)
	v_pk_mul_f32 v[10:11], v[10:11], v[106:107]
	s_waitcnt lgkmcnt(1)
	v_pk_mul_f32 v[6:7], v[6:7], v[110:111]
	s_waitcnt lgkmcnt(0)
	v_pk_mul_f32 v[2:3], v[2:3], v[114:115]
	v_pk_mul_f32 v[12:13], v[12:13], v[100:101]
	v_pk_mul_f32 v[8:9], v[8:9], v[104:105]
	v_pk_mul_f32 v[4:5], v[4:5], v[108:109]
	v_pk_mul_f32 v[0:1], v[0:1], v[112:113]
	v_pk_mul_f32 v[62:63], v[62:63], v[102:103]
	v_pk_mul_f32 v[58:59], v[58:59], v[106:107]
	v_pk_mul_f32 v[54:55], v[54:55], v[110:111]
	v_pk_mul_f32 v[50:51], v[50:51], v[114:115]
	v_pk_mul_f32 v[60:61], v[60:61], v[100:101]
	v_pk_mul_f32 v[56:57], v[56:57], v[104:105]
	v_pk_mul_f32 v[52:53], v[52:53], v[108:109]
	v_pk_mul_f32 v[48:49], v[48:49], v[112:113]
	v_pk_mul_f32 v[46:47], v[46:47], v[102:103]
	v_pk_mul_f32 v[42:43], v[42:43], v[106:107]
	v_pk_mul_f32 v[38:39], v[38:39], v[110:111]
	v_pk_mul_f32 v[34:35], v[34:35], v[114:115]
	v_pk_mul_f32 v[44:45], v[44:45], v[100:101]
	v_pk_mul_f32 v[40:41], v[40:41], v[104:105]
	v_pk_mul_f32 v[36:37], v[36:37], v[108:109]
	v_pk_mul_f32 v[32:33], v[32:33], v[112:113]
	v_pk_mul_f32 v[30:31], v[30:31], v[102:103]
	v_pk_mul_f32 v[26:27], v[26:27], v[106:107]
	v_pk_mul_f32 v[22:23], v[22:23], v[110:111]
	v_pk_mul_f32 v[18:19], v[18:19], v[114:115]
	v_pk_mul_f32 v[28:29], v[28:29], v[100:101]
	v_pk_mul_f32 v[24:25], v[24:25], v[104:105]
	v_pk_mul_f32 v[20:21], v[20:21], v[108:109]
	v_pk_mul_f32 v[16:17], v[16:17], v[112:113]

; __device__ __forceinline__ void finishSM(f32x16& p0, f32x16& p1, float alpha, float& l_reg, bf16x8& pa0, bf16x8& pa1, bf16x8& pa2, bf16x8& pa3) {
;     for (int r = 0; r < 16; ++r) p1[r] = __builtin_amdgcn_exp2f(p1[r]);
;     float ps = 0; for (int r = 0; r < 16; ++r) ps += p0[r]; for (int r = 0; r < 16; ++r) ps += p1[r];
;     { auto rr = __builtin_amdgcn_permlane32_swap(__float_as_uint(ps), __float_as_uint(ps), false, false);
;       ps = __uint_as_float(rr[0]) + __uint_as_float(rr[1]); }
;     l_reg = l_reg * alpha + ps;
;     ...
;     PK4(p0, 0, pa0); PK4(p0, 8, pa1); PK4(p1, 0, pa2); PK4(p1, 8, pa3);
;     ...
; }
; template <int KB>
; __device__ __forceinline__ void qkt(f32x16& p0, f32x16& p1, const char* K_lds, const float* bias_l, int r32, int hi, const bf16x8* qr) {
;     const f32x4* bl = reinterpret_cast<const f32x4*>(bias_l + KB * 64);
; #pragma unroll
;     for (int g = 0; g < 4; ++g) { const f32x4 b0 = bl[2 * g + hi], b1 = bl[8 + 2 * g + hi];
;         p0[4 * g + 0] = b0[0]; p0[4 * g + 1] = b0[1]; p0[4 * g + 2] = b0[2]; p0[4 * g + 3] = b0[3];
;         p1[4 * g + 0] = b1[0]; p1[4 * g + 1] = b1[1]; p1[4 * g + 2] = b1[2]; p1[4 * g + 3] = b1[3]; }
;     const char* kb[4];
; #pragma unroll
;     for (int dd = 0; dd < 4; ++dd) kb[dd] = K_lds + KB * SHM_K + KSWZ(r32, (dd * 16 + hi * 8) * 2);
; #pragma unroll
;     for (int d0 = 0; d0 < 8; ++d0) { const char* a = kb[d0 & 3] + (d0 >> 2) * 128;
;         bf16x8 b0 = *reinterpret_cast<const bf16x8*>(a);
;         bf16x8 b1 = *reinterpret_cast<const bf16x8*>(a + 32 * 256);
;         p0 = __builtin_amdgcn_mfma_f32_32x32x16_bf16(b0, qr[d0], p0, 0, 0, 0);
;         p1 = __builtin_amdgcn_mfma_f32_32x32x16_bf16(b1, qr[d0], p1, 0, 0, 0); }
; }
.LBB0_267:
	ds_read_b128 v[112:115], v219
	ds_read_b128 v[116:119], v219 offset:32
	ds_read_b128 v[96:99], v219 offset:128
	ds_read_b128 v[100:103], v219 offset:160
	ds_read_b128 v[120:123], v219 offset:64
	ds_read_b128 v[104:107], v219 offset:192
	ds_read_b128 v[124:127], v219 offset:96
	ds_read_b128 v[108:111], v219 offset:224
	ds_read_b128 v[196:199], v214 offset:32768
	ds_read_b128 v[242:245], v214 offset:40960
	ds_read_b128 v[246:249], v215 offset:32768
	ds_read_b128 v[250:253], v215 offset:40960
	v_exp_f32_e32 v85, v85
	v_exp_f32_e32 v86, v86
	v_exp_f32_e32 v87, v87
	v_exp_f32_e32 v88, v88
	v_exp_f32_e32 v89, v89
	v_exp_f32_e32 v90, v90
	v_exp_f32_e32 v91, v91
	v_exp_f32_e32 v92, v92
	v_exp_f32_e32 v83, v95
	v_exp_f32_e32 v95, v176
	v_add_f32_e32 v176, 0, v64
	v_add_f32_e32 v176, v65, v176
	v_add_f32_e32 v176, v66, v176
	v_add_f32_e32 v176, v67, v176
	v_add_f32_e32 v176, v68, v176
	v_add_f32_e32 v176, v69, v176
	v_add_f32_e32 v176, v70, v176
	v_add_f32_e32 v176, v71, v176
	v_add_f32_e32 v176, v72, v176
	v_add_f32_e32 v176, v73, v176
	v_add_f32_e32 v176, v74, v176
	v_add_f32_e32 v176, v75, v176
	v_exp_f32_e32 v80, v84
	v_add_f32_e32 v176, v76, v176
	v_exp_f32_e32 v81, v93
	v_add_f32_e32 v176, v77, v176
	v_exp_f32_e32 v82, v94
	v_add_f32_e32 v176, v78, v176
	v_add_f32_e32 v176, v79, v176
	v_exp_f32_e32 v84, v177
	v_add_f32_e32 v176, v80, v176
	v_add_f32_e32 v176, v81, v176
	v_add_f32_e32 v176, v82, v176
	v_add_f32_e32 v176, v83, v176
	v_add_f32_e32 v176, v84, v176
	v_add_f32_e32 v176, v85, v176
	v_add_f32_e32 v176, v86, v176
	v_add_f32_e32 v176, v87, v176
	v_add_f32_e32 v176, v88, v176
	v_exp_f32_e32 v93, v178
	v_add_f32_e32 v176, v89, v176
	v_exp_f32_e32 v94, v179
	s_waitcnt lgkmcnt(3)
	v_mfma_f32_32x32x16_bf16 v[112:127], v[196:199], v[156:159], v[112:127]
	v_add_f32_e32 v176, v90, v176
	v_add_f32_e32 v176, v91, v176
	v_add_f32_e32 v176, v92, v176
	s_waitcnt lgkmcnt(2)
	v_mfma_f32_32x32x16_bf16 v[96:111], v[242:245], v[156:159], v[96:111]
	v_add_f32_e32 v176, v93, v176
	v_add_f32_e32 v176, v94, v176
	v_add_f32_e32 v240, v95, v176
	ds_read_b128 v[196:199], v213 offset:32768
	ds_read_b128 v[242:245], v213 offset:40960
	s_waitcnt lgkmcnt(3)
	v_mfma_f32_32x32x16_bf16 v[112:127], v[246:249], v[152:155], v[112:127]
	v_mov_b32_e32 v241, v240
	s_nop 1
	v_permlane32_swap_b32_e32 v240, v241
	s_waitcnt lgkmcnt(2)
	v_mfma_f32_32x32x16_bf16 v[96:111], v[250:253], v[152:155], v[96:111]
	v_cvt_pk_bf16_f32 v64, v64, v65
	v_cvt_pk_bf16_f32 v65, v66, v67
	v_cvt_pk_bf16_f32 v66, v68, v69
	ds_read_b128 v[246:249], v212 offset:32768
	ds_read_b128 v[250:253], v212 offset:40960
	s_waitcnt lgkmcnt(3)
	v_mfma_f32_32x32x16_bf16 v[112:127], v[196:199], v[148:151], v[112:127]
	v_cvt_pk_bf16_f32 v67, v70, v71
	v_cvt_pk_bf16_f32 v68, v72, v73
	v_cvt_pk_bf16_f32 v69, v74, v75
	s_waitcnt lgkmcnt(2)
	v_mfma_f32_32x32x16_bf16 v[96:111], v[242:245], v[148:151], v[96:111]
	v_cvt_pk_bf16_f32 v70, v76, v77
	v_cvt_pk_bf16_f32 v71, v78, v79
	v_cvt_pk_bf16_f32 v72, v80, v81
	ds_read_b128 v[196:199], v214 offset:32896
	ds_read_b128 v[242:245], v214 offset:41088
	s_waitcnt lgkmcnt(3)
	v_mfma_f32_32x32x16_bf16 v[112:127], v[246:249], v[144:147], v[112:127]
	v_cvt_pk_bf16_f32 v73, v82, v83
	v_cvt_pk_bf16_f32 v74, v84, v85
	v_cvt_pk_bf16_f32 v75, v86, v87
	s_waitcnt lgkmcnt(2)
	v_mfma_f32_32x32x16_bf16 v[96:111], v[250:253], v[144:147], v[96:111]
	v_cvt_pk_bf16_f32 v76, v88, v89
	v_cvt_pk_bf16_f32 v77, v90, v91
	v_cvt_pk_bf16_f32 v78, v92, v93
	ds_read_b128 v[246:249], v215 offset:32896
	ds_read_b128 v[250:253], v215 offset:41088
	s_waitcnt lgkmcnt(3)
	v_mfma_f32_32x32x16_bf16 v[112:127], v[196:199], v[140:143], v[112:127]
	v_cvt_pk_bf16_f32 v79, v94, v95
	s_nop 0
	v_permlane32_swap_b32_e32 v64, v66
	s_waitcnt lgkmcnt(2)
	v_mfma_f32_32x32x16_bf16 v[96:111], v[242:245], v[140:143], v[96:111]
	v_permlane32_swap_b32_e32 v65, v67
	v_permlane32_swap_b32_e32 v68, v70
	v_permlane32_swap_b32_e32 v69, v71
	ds_read_b128 v[196:199], v213 offset:32896
	ds_read_b128 v[242:245], v213 offset:41088
	s_waitcnt lgkmcnt(3)
	v_mfma_f32_32x32x16_bf16 v[112:127], v[246:249], v[136:139], v[112:127]
	v_permlane32_swap_b32_e32 v72, v74
	v_permlane32_swap_b32_e32 v73, v75
	v_permlane32_swap_b32_e32 v76, v78
	s_waitcnt lgkmcnt(2)
	v_mfma_f32_32x32x16_bf16 v[96:111], v[250:253], v[136:139], v[96:111]
	v_permlane32_swap_b32_e32 v77, v79
	ds_read_b128 v[246:249], v212 offset:32896
	ds_read_b128 v[250:253], v212 offset:41088
	s_waitcnt lgkmcnt(3)
	v_mfma_f32_32x32x16_bf16 v[112:127], v[196:199], v[132:135], v[112:127]
	s_waitcnt lgkmcnt(2)
	v_mfma_f32_32x32x16_bf16 v[96:111], v[242:245], v[132:135], v[96:111]
	ds_read_b64_tr_b16 v[196:197], v209 offset:0x4000
	ds_read_b64_tr_b16 v[198:199], v209 offset:0x4800
	ds_read_b64_tr_b16 v[242:243], v209 offset:0x5000
	ds_read_b64_tr_b16 v[244:245], v209 offset:0x5800
	s_waitcnt lgkmcnt(5)
	v_mfma_f32_32x32x16_bf16 v[112:127], v[246:249], v[128:131], v[112:127]
	s_waitcnt lgkmcnt(4)
	v_mfma_f32_32x32x16_bf16 v[96:111], v[250:253], v[128:131], v[96:111]
	ds_read_b64_tr_b16 v[246:247], v209 offset:0x6000
	ds_read_b64_tr_b16 v[248:249], v209 offset:0x6800
	ds_read_b64_tr_b16 v[250:251], v209 offset:0x7000
	ds_read_b64_tr_b16 v[252:253], v209 offset:0x7800
	s_add_i32 s12, s96, -1
	s_cmp_le_i32 s12, s84
	s_cbranch_scc1 .Lhs2_nomask
; __device__ __forceinline__ void mask_tile(f32x16& p0, f32x16& p1, int dq, unsigned W) {
;     const float NEG = -__builtin_inff();
; #pragma unroll
;     for (int r = 0; r < 16; ++r) {
;         const int c = (r & 3) + 8 * (r >> 2);
;         if ((unsigned)(dq - c) >= W) p0[r] = NEG;
;         if ((unsigned)(dq - c - 32) >= W) p1[r] = NEG;
;     }
; }
	v_cmp_gt_i32_e64 s[72:73], 26, v223
	v_cmp_gt_i32_e64 s[74:75], 27, v223
	v_cmp_gt_i32_e64 s[70:71], 25, v223
	s_and_b64 s[72:73], s[74:75], s[72:73]
	v_cmp_gt_i32_e64 s[68:69], 24, v223
	s_and_b64 s[70:71], s[72:73], s[70:71]
	v_cmp_gt_i32_e64 s[66:67], 19, v223
	s_and_b64 s[68:69], s[70:71], s[68:69]
	v_cmp_gt_i32_e64 s[64:65], 18, v223
	s_and_b64 s[66:67], s[68:69], s[66:67]
	v_cmp_gt_i32_e64 s[62:63], 17, v223
	s_and_b64 s[64:65], s[66:67], s[64:65]
	v_cmp_gt_i32_e64 s[60:61], 16, v223
	s_and_b64 s[62:63], s[64:65], s[62:63]
	v_cmp_gt_i32_e64 s[58:59], 11, v223
	s_and_b64 s[60:61], s[62:63], s[60:61]
	v_cmp_gt_i32_e64 s[56:57], 10, v223
	s_and_b64 s[58:59], s[60:61], s[58:59]
	v_cmp_gt_i32_e64 s[54:55], 9, v223
	s_and_b64 s[56:57], s[58:59], s[56:57]
	v_cmp_gt_i32_e64 s[52:53], 8, v223
	s_and_b64 s[54:55], s[56:57], s[54:55]
	v_cmp_gt_i32_e64 s[50:51], 3, v223
	s_and_b64 s[52:53], s[54:55], s[52:53]
	v_cmp_gt_i32_e64 s[48:49], 2, v223
	s_and_b64 s[50:51], s[52:53], s[50:51]
	v_cmp_gt_i32_e64 s[46:47], 1, v223
	s_and_b64 s[48:49], s[50:51], s[48:49]
	v_cmp_gt_i32_e64 s[44:45], 0, v223
	s_and_b64 s[46:47], s[48:49], s[46:47]
	s_and_b64 s[44:45], s[46:47], s[44:45]
	v_cmp_gt_i32_e64 s[40:41], 58, v223
	v_cndmask_b32_e64 v112, v112, v205, s[44:45]
	v_cmp_gt_i32_e64 s[44:45], 59, v223
	v_cmp_gt_i32_e64 s[38:39], 57, v223
	s_and_b64 s[40:41], s[44:45], s[40:41]
	v_cmp_gt_i32_e64 s[36:37], 56, v223
	s_and_b64 s[38:39], s[40:41], s[38:39]
	v_cmp_gt_i32_e64 s[34:35], 51, v223
	s_and_b64 s[36:37], s[38:39], s[36:37]
	v_cmp_gt_i32_e64 s[30:31], 50, v223
	s_and_b64 s[34:35], s[36:37], s[34:35]
	v_cmp_gt_i32_e64 s[28:29], 49, v223
	s_and_b64 s[30:31], s[34:35], s[30:31]
	v_cmp_gt_i32_e64 s[26:27], 48, v223
	s_and_b64 s[28:29], s[30:31], s[28:29]
	v_cmp_gt_i32_e64 s[24:25], 43, v223
	s_and_b64 s[26:27], s[28:29], s[26:27]
	v_cmp_gt_i32_e64 s[22:23], 42, v223
	s_and_b64 s[24:25], s[26:27], s[24:25]
	v_cmp_gt_i32_e64 s[20:21], 41, v223
	s_and_b64 s[22:23], s[24:25], s[22:23]
	v_cmp_gt_i32_e64 s[18:19], 40, v223
	s_and_b64 s[20:21], s[22:23], s[20:21]
	v_cmp_gt_i32_e64 s[16:17], 35, v223
	s_and_b64 s[18:19], s[20:21], s[18:19]
	v_cmp_gt_i32_e64 s[14:15], 34, v223
	s_and_b64 s[16:17], s[18:19], s[16:17]
	v_cmp_gt_i32_e64 s[12:13], 33, v223
	s_and_b64 s[14:15], s[16:17], s[14:15]
	v_cmp_gt_i32_e32 vcc, 32, v223
	s_and_b64 s[12:13], s[14:15], s[12:13]
	s_and_b64 vcc, s[12:13], vcc
	v_cndmask_b32_e64 v127, v127, v205, s[74:75]
	v_cndmask_b32_e64 v126, v126, v205, s[72:73]
	v_cndmask_b32_e64 v125, v125, v205, s[70:71]
	v_cndmask_b32_e64 v124, v124, v205, s[68:69]
	v_cndmask_b32_e64 v123, v123, v205, s[66:67]
	v_cndmask_b32_e64 v122, v122, v205, s[64:65]
	v_cndmask_b32_e64 v121, v121, v205, s[62:63]
	v_cndmask_b32_e64 v120, v120, v205, s[60:61]
	v_cndmask_b32_e64 v119, v119, v205, s[58:59]
	v_cndmask_b32_e64 v118, v118, v205, s[56:57]
	v_cndmask_b32_e64 v117, v117, v205, s[54:55]
	v_cndmask_b32_e64 v116, v116, v205, s[52:53]
	v_cndmask_b32_e64 v115, v115, v205, s[50:51]
	v_cndmask_b32_e64 v114, v114, v205, s[48:49]
	v_cndmask_b32_e64 v113, v113, v205, s[46:47]
	v_cndmask_b32_e64 v111, v111, v205, s[44:45]
	v_cndmask_b32_e64 v110, v110, v205, s[40:41]
	v_cndmask_b32_e64 v109, v109, v205, s[38:39]
	v_cndmask_b32_e64 v108, v108, v205, s[36:37]
	v_cndmask_b32_e64 v107, v107, v205, s[34:35]
	v_cndmask_b32_e64 v106, v106, v205, s[30:31]
	v_cndmask_b32_e64 v105, v105, v205, s[28:29]
	v_cndmask_b32_e64 v104, v104, v205, s[26:27]
	v_cndmask_b32_e64 v103, v103, v205, s[24:25]
	v_cndmask_b32_e64 v102, v102, v205, s[22:23]
	v_cndmask_b32_e64 v101, v101, v205, s[20:21]
	v_cndmask_b32_e64 v100, v100, v205, s[18:19]
	v_cndmask_b32_e64 v99, v99, v205, s[16:17]
	v_cndmask_b32_e64 v98, v98, v205, s[14:15]
	v_cndmask_b32_e64 v97, v97, v205, s[12:13]
	v_cndmask_b32_e32 v96, v96, v205, vcc
; __device__ __forceinline__ void partialSM(f32x16& p0, f32x16& p1, float& m_reg, float& mn, float& alpha) {
;     float pmax = p0[0]; for (int r = 1; r < 16; ++r) pmax = fmaxf(pmax, p0[r]); for (int r = 0; r < 16; ++r) pmax = fmaxf(pmax, p1[r]);
;     { auto rr = __builtin_amdgcn_permlane32_swap(__float_as_uint(pmax), __float_as_uint(pmax), false, false);
;       pmax = fmaxf(__uint_as_float(rr[0]), __uint_as_float(rr[1])); }
;     constexpr float C2 = 1.4426950408889634f * SCALE;
;     if (__builtin_expect(__all((pmax - m_reg) * SCALE <= THR), 1)) { mn = m_reg; alpha = 1.f; }
;     else { mn = fmaxf(m_reg, pmax); alpha = __builtin_amdgcn_exp2f((m_reg - mn) * C2); m_reg = mn; }
;     const float mnL = -mn * C2;
;     for (int r = 0; r < 16; ++r) p0[r] = fmaf(p0[r], C2, mnL); for (int r = 0; r < 16; ++r) p1[r] = fmaf(p1[r], C2, mnL);
;     for (int r = 0; r < 16; ++r) p0[r] = __builtin_amdgcn_exp2f(p0[r]);
; }
; template <int VB>
; __device__ __forceinline__ void pv_tile(f32x16* o, int vb0, bf16x8 pa0, bf16x8 pa1, bf16x8 pa2, bf16x8 pa3) {
;     ...
;     PV_D0(0); PV_D0(1); PV_D0(2); PV_D0(3);
.Lhs2_nomask:
	s_waitcnt lgkmcnt(6)
	v_mfma_f32_32x32x16_bf16 v[0:15], v[64:67], v[196:199], v[0:15]
	ds_read_b64_tr_b16 v[196:197], v209 offset:0x4200
	ds_read_b64_tr_b16 v[198:199], v209 offset:0x4a00
	s_waitcnt lgkmcnt(6)
	v_mfma_f32_32x32x16_bf16 v[0:15], v[68:71], v[242:245], v[0:15]
	ds_read_b64_tr_b16 v[242:243], v209 offset:0x5200
	ds_read_b64_tr_b16 v[244:245], v209 offset:0x5a00
	s_waitcnt lgkmcnt(6)
	v_mfma_f32_32x32x16_bf16 v[0:15], v[72:75], v[246:249], v[0:15]
	ds_read_b64_tr_b16 v[246:247], v209 offset:0x6200
	ds_read_b64_tr_b16 v[248:249], v209 offset:0x6a00
	v_max_f32_e32 v176, v113, v113
	v_max_f32_e32 v177, v112, v112
	v_max_f32_e32 v176, v177, v176
	v_max3_f32 v176, v176, v114, v115
	v_max3_f32 v176, v176, v116, v117
	v_max3_f32 v176, v176, v118, v119
	v_max3_f32 v176, v176, v120, v121
	v_max3_f32 v176, v176, v122, v123
	s_waitcnt lgkmcnt(6)
	v_mfma_f32_32x32x16_bf16 v[0:15], v[76:79], v[250:253], v[0:15]
	ds_read_b64_tr_b16 v[250:251], v209 offset:0x7200
	ds_read_b64_tr_b16 v[252:253], v209 offset:0x7a00
	v_max3_f32 v176, v176, v124, v125
	v_max3_f32 v176, v176, v126, v127
	v_max3_f32 v176, v176, v96, v97
	v_max3_f32 v176, v176, v98, v99
	v_max3_f32 v176, v176, v100, v101
	v_max3_f32 v176, v176, v102, v103
	v_max3_f32 v176, v176, v104, v105
	v_max3_f32 v176, v176, v106, v107
	s_waitcnt lgkmcnt(6)
	v_mfma_f32_32x32x16_bf16 v[48:63], v[64:67], v[196:199], v[48:63]
	ds_read_b64_tr_b16 v[196:197], v209 offset:0x4400
	ds_read_b64_tr_b16 v[198:199], v209 offset:0x4c00
	v_max3_f32 v176, v176, v108, v109
	v_max3_f32 v176, v176, v110, v111
	v_mov_b32_e32 v177, v176
	s_nop 1
	v_permlane32_swap_b32_e32 v176, v177
	v_max_f32_e32 v177, v177, v177
	v_max_f32_e32 v176, v176, v176
	v_max_f32_e32 v176, v176, v177
	s_waitcnt lgkmcnt(6)
	v_mfma_f32_32x32x16_bf16 v[48:63], v[68:71], v[242:245], v[48:63]
	ds_read_b64_tr_b16 v[242:243], v209 offset:0x5400
	ds_read_b64_tr_b16 v[244:245], v209 offset:0x5c00
	v_sub_f32_e32 v177, v176, v227
	v_mul_f32_e32 v177, 0x3db504f3, v177
	v_cmp_ge_f32_e32 vcc, s97, v177
	s_cmp_eq_u64 vcc, exec
	s_cselect_b64 s[12:13], -1, 0
	v_max_f32_e32 v177, v227, v227
	v_max_f32_e32 v179, v177, v176
	v_cndmask_b32_e64 v176, v179, v227, s[12:13]
	v_mul_f32_e32 v178, 0xbe0293ee, v176
	s_waitcnt lgkmcnt(6)
	v_mfma_f32_32x32x16_bf16 v[48:63], v[72:75], v[246:249], v[48:63]
	ds_read_b64_tr_b16 v[246:247], v209 offset:0x6400
	ds_read_b64_tr_b16 v[248:249], v209 offset:0x6c00
	v_mov_b32_e32 v95, v178
	v_fmamk_f32 v80, v112, 0x3e0293ee, v178
	v_fmamk_f32 v81, v113, 0x3e0293ee, v178
	v_fmamk_f32 v82, v114, 0x3e0293ee, v178
	v_fmamk_f32 v83, v115, 0x3e0293ee, v178
	v_fmamk_f32 v84, v116, 0x3e0293ee, v178
	v_fmamk_f32 v85, v117, 0x3e0293ee, v178
	v_fmamk_f32 v86, v118, 0x3e0293ee, v178
	s_waitcnt lgkmcnt(6)
	v_mfma_f32_32x32x16_bf16 v[48:63], v[76:79], v[250:253], v[48:63]
	ds_read_b64_tr_b16 v[250:251], v209 offset:0x7400
	ds_read_b64_tr_b16 v[252:253], v209 offset:0x7c00
	v_fmamk_f32 v87, v119, 0x3e0293ee, v178
	v_fmamk_f32 v88, v120, 0x3e0293ee, v178
	v_fmamk_f32 v89, v121, 0x3e0293ee, v178
	v_fmamk_f32 v90, v122, 0x3e0293ee, v178
	v_fmamk_f32 v91, v123, 0x3e0293ee, v178
	v_fmamk_f32 v92, v124, 0x3e0293ee, v178
	v_fmamk_f32 v93, v125, 0x3e0293ee, v178
	v_fmamk_f32 v94, v126, 0x3e0293ee, v178
	s_waitcnt lgkmcnt(6)
	v_mfma_f32_32x32x16_bf16 v[32:47], v[64:67], v[196:199], v[32:47]
	ds_read_b64_tr_b16 v[196:197], v209 offset:0x4600
	ds_read_b64_tr_b16 v[198:199], v209 offset:0x4e00
	v_fmac_f32_e32 v95, 0x3e0293ee, v127
	v_fmamk_f32 v126, v96, 0x3e0293ee, v178
	v_fmamk_f32 v127, v97, 0x3e0293ee, v178
	v_fmamk_f32 v112, v110, 0x3e0293ee, v178
	v_fmamk_f32 v113, v111, 0x3e0293ee, v178
	v_fmamk_f32 v114, v108, 0x3e0293ee, v178
	v_fmamk_f32 v115, v109, 0x3e0293ee, v178
	v_fmamk_f32 v116, v106, 0x3e0293ee, v178
	s_waitcnt lgkmcnt(6)
	v_mfma_f32_32x32x16_bf16 v[32:47], v[68:71], v[242:245], v[32:47]
	ds_read_b64_tr_b16 v[242:243], v209 offset:0x5600
	ds_read_b64_tr_b16 v[244:245], v209 offset:0x5e00
	v_fmamk_f32 v117, v107, 0x3e0293ee, v178
	v_fmamk_f32 v118, v104, 0x3e0293ee, v178
	v_fmamk_f32 v119, v105, 0x3e0293ee, v178
	v_fmamk_f32 v120, v102, 0x3e0293ee, v178
	v_fmamk_f32 v121, v103, 0x3e0293ee, v178
	v_fmamk_f32 v122, v100, 0x3e0293ee, v178
	v_fmamk_f32 v123, v101, 0x3e0293ee, v178
	v_fmamk_f32 v124, v98, 0x3e0293ee, v178
	s_waitcnt lgkmcnt(6)
	v_mfma_f32_32x32x16_bf16 v[32:47], v[72:75], v[246:249], v[32:47]
	ds_read_b64_tr_b16 v[246:247], v209 offset:0x6600
	ds_read_b64_tr_b16 v[248:249], v209 offset:0x6e00
	v_fmamk_f32 v125, v99, 0x3e0293ee, v178
	v_sub_f32_e32 v96, v227, v179
	v_mul_f32_e32 v96, 0x3e0293ee, v96
	v_exp_f32_e32 v96, v96
	s_nop 0
	v_cndmask_b32_e64 v96, v96, 1.0, s[12:13]
	v_exp_f32_e32 v237, v80
	s_waitcnt lgkmcnt(6)
	v_mfma_f32_32x32x16_bf16 v[32:47], v[76:79], v[250:253], v[32:47]
	ds_read_b64_tr_b16 v[250:251], v209 offset:0x7600
	ds_read_b64_tr_b16 v[252:253], v209 offset:0x7e00
	v_exp_f32_e32 v239, v81
	v_exp_f32_e32 v235, v82
	v_exp_f32_e32 v238, v83
	v_exp_f32_e32 v234, v84
	s_waitcnt lgkmcnt(6)
	v_mfma_f32_32x32x16_bf16 v[16:31], v[64:67], v[196:199], v[16:31]
	v_exp_f32_e32 v236, v85
	v_exp_f32_e32 v232, v86
	v_exp_f32_e32 v233, v87
	v_exp_f32_e32 v228, v88
	s_waitcnt lgkmcnt(4)
	v_mfma_f32_32x32x16_bf16 v[16:31], v[68:71], v[242:245], v[16:31]
	v_exp_f32_e32 v231, v89
	v_exp_f32_e32 v179, v90
	v_exp_f32_e32 v229, v91
	v_exp_f32_e32 v177, v92
	s_waitcnt lgkmcnt(2)
	v_mfma_f32_32x32x16_bf16 v[16:31], v[72:75], v[246:249], v[16:31]
	v_exp_f32_e32 v230, v93
	v_exp_f32_e32 v178, v94
	v_exp_f32_e32 v227, v95
	s_waitcnt lgkmcnt(0)
	v_mfma_f32_32x32x16_bf16 v[16:31], v[76:79], v[250:253], v[16:31]
	v_readlane_b32 s54, v255, 30
	v_readlane_b32 s55, v255, 31
	s_andn2_b64 vcc, exec, s[42:43]
	s_cbranch_vccnz .Lhs2_bar1
	s_waitcnt vmcnt(0)
	s_and_b64 vcc, exec, s[10:11]
	ds_write_b128 v208, v[164:167] offset:49152
	ds_write_b128 v208, v[172:175] offset:57344
	s_cbranch_vccnz .Lhs2_bar1
	s_mov_b32 s10, 0x667f3bcd
	v_add_f64 v[64:65], s[94:95], -v[188:189]
	s_mov_b32 s11, 0x4026a09e
	v_mul_f64 v[64:65], v[64:65], s[10:11]
	v_cvt_f32_f64_e32 v64, v[64:65]
	ds_write_b32 v221, v64 offset:256
.Lhs2_bar1:
	s_barrier
	s_andn2_b64 vcc, exec, s[42:43]
	s_cbranch_vccnz .LBB0_272
	ds_write_b128 v216, v[160:163] offset:16384
	ds_write_b128 v217, v[168:171] offset:16384
.LBB0_272:
	s_waitcnt vmcnt(3)
	v_mov_b32_e32 v160, v96
	v_cmp_gt_f32_e32 vcc, 1.0, v160
	s_cbranch_vccz .LBB0_252
	s_and_saveexec_b64 s[10:11], s[8:9]
	s_cbranch_execz .LBB0_251
	ds_write_b32 v222, v160 offset:128
	s_branch .LBB0_251
